# attention tile loops: LDS-DMA via saddr+voffset (no 64-bit VALU address adds), hoisted loop-invariant LDS fragment addresses; on top of bisection/sp4/nt changes
# speedup vs baseline: 1.1757x; 1.0015x over previous
; DI int pi_row(int r) { return (r & 3) | (((r >> 3) & 1) << 2) | (((r >> 2) & 1) << 3) | (r & 16); }
; DI void attn_job(const Args& a, unsigned char* wsh, LAS unsigned char* wl, int type, int b, int qt, int hd, const int tid) {
;     ...
;     AttnCtx c; c.wl = wl; c.lut = lut; c.krs = 1;
; #pragma unroll
;     for (int j = 0; j < 4; ++j) {
;         const int rk = 8 * j + (lane >> 3), ck = (lane & 7) ^ ((rk >> 1) & 7);
;         c.koff[j] = (unsigned)(pi_row(rk) * RM_LD + ck * 8) * 2u;
;         const int rv = 16 * j + (lane >> 2), cv = (lane & 3) ^ ((rv >> 2) & 3);
;         c.voff[j] = (unsigned)(rv * MTOK + cv * 8) * 2u;
;         c.kfo[j] = r * 128 + (((2 * j + h) ^ ((r >> 1) & 7)) * 16);
;     }
; #pragma unroll
;     for (int mt = 0; mt < 2; ++mt)
; #pragma unroll
;         for (int s = 0; s < 2; ++s) c.vfo[mt][s] = (32 * mt + r) * 64 + (((2 * s + h) ^ ((r >> 2) & 3)) * 16);
.LBB0_266:
	s_and_b64 vcc, exec, s[0:1]
	s_cbranch_vccz .LBB0_366
	v_lshrrev_b32_e32 v4, 2, v210
	v_bfe_u32 v3, v210, 3, 3
	v_and_b32_e32 v5, 8, v4
	v_bfe_u32 v8, v210, 4, 2
	v_xor_b32_e32 v8, v8, v210
	v_and_or_b32 v9, v3, 3, v5
	v_mul_u32_u24_e32 v9, 0xb00, v9
	v_lshlrev_b32_e32 v8, 3, v8
	v_and_or_b32 v8, v8, 56, v9
	v_or3_b32 v9, v3, v5, 4
	v_or_b32_e32 v3, 24, v3
	v_lshlrev_b32_e32 v116, 1, v8
	v_lshrrev_b32_e32 v8, 4, v210
	v_lshrrev_b32_e32 v10, 1, v3
	v_readfirstlane_b32 s0, v210
	v_lshlrev_b32_e32 v7, 4, v210
	v_bitop3_b32 v8, v8, v210, 4 bitop3:0x36
	v_xor_b32_e32 v10, v10, v210
	v_and_or_b32 v3, v3, 19, v5
	s_ashr_i32 s48, s0, 6
	v_and_b32_e32 v0, 63, v210
	v_lshlrev_b32_e32 v6, 15, v210
	v_bitop3_b32 v7, v7, 48, v210 bitop3:0x48
	s_mov_b32 s1, 0x1e0000
	v_mul_u32_u24_e32 v9, 0xb00, v9
	v_lshlrev_b32_e32 v8, 3, v8
	v_mul_u32_u24_e32 v3, 0xb00, v3
	v_lshlrev_b32_e32 v5, 3, v10
	v_readlane_b32 s4, v251, 19
	s_lshl_b32 s0, s48, 14
	v_bfe_u32 v2, v210, 5, 1
	v_and_or_b32 v114, v6, s1, v7
	v_bfe_u32 v7, v210, 1, 3
	v_and_or_b32 v8, v8, 56, v9
	v_and_or_b32 v3, v5, 56, v3
	v_lshlrev_b32_e32 v0, 4, v0
	v_readlane_b32 s5, v251, 20
	s_add_i32 s49, s0, 0
	v_lshlrev_b32_e32 v118, 1, v8
	v_bitop3_b32 v8, v2, v7, 2 bitop3:0x36
	v_bitop3_b32 v9, v2, v7, 4 bitop3:0x36
	v_lshl_add_u32 v126, v3, 1, v238
	v_bitop3_b32 v3, v2, v7, 6 bitop3:0x36
	v_lshl_add_u64 v[130:131], s[4:5], 0, v[0:1]
	v_readlane_b32 s4, v254, 55
	v_and_b32_e32 v7, 3, v210
	v_add_u32_e32 v143, s49, v0
	v_lshlrev_b32_e32 v0, 4, v2
	v_readlane_b32 s5, v254, 56
	v_cmp_eq_u32_e64 s[38:39], 2, v7
	v_cmp_eq_u32_e64 s[40:41], 1, v7
	v_lshl_add_u64 v[132:133], s[4:5], 0, v[0:1]
	v_cndmask_b32_e64 v0, 3, 2, s[38:39]
	v_cndmask_b32_e64 v0, v0, 1, s[40:41]
	v_cmp_eq_u32_e64 s[42:43], 0, v7
	v_lshrrev_b32_e32 v6, 1, v210
	v_bfe_u32 v5, v210, 2, 2
	v_cndmask_b32_e64 v134, v0, 0, s[42:43]
	v_cndmask_b32_e64 v0, 7, 6, s[38:39]
	v_cndmask_b32_e64 v0, v0, 5, s[40:41]
	v_lshl_add_u32 v157, v3, 4, s49
	v_and_b32_e32 v3, 64, v233
	v_lshlrev_b32_e32 v137, 3, v2
	v_bitop3_b32 v6, v2, v6, 7 bitop3:0x78
	v_bitop3_b32 v4, v2, v4, 3 bitop3:0x78
	v_bitop3_b32 v5, v2, v5, 2 bitop3:0x36
	v_cndmask_b32_e64 v136, v0, 4, s[42:43]
	v_cndmask_b32_e64 v0, 11, 10, s[38:39]
	v_lshlrev_b32_e32 v142, 2, v2
	v_xor_b32_e32 v2, 32, v233
	v_add_u32_e32 v3, 64, v3
	v_cndmask_b32_e64 v0, v0, 9, s[40:41]
	v_cmp_lt_i32_e32 vcc, v2, v3
	v_and_b32_e32 v135, 31, v210
	v_cndmask_b32_e64 v138, v0, 8, s[42:43]
	v_cndmask_b32_e64 v0, 15, 14, s[38:39]
	v_cndmask_b32_e32 v2, v233, v2, vcc
	v_cndmask_b32_e64 v0, v0, 13, s[40:41]
	v_readlane_b32 s4, v251, 25
	v_lshlrev_b32_e32 v160, 2, v2
	v_sub_u32_e32 v2, v135, v7
	v_cndmask_b32_e64 v140, v0, 12, s[42:43]
	v_and_b32_e32 v0, 32, v210
	v_readlane_b32 s5, v251, 26
	v_sub_u32_e32 v164, v2, v137
	v_lshl_or_b32 v2, v135, 2, s0
	v_lshl_add_u64 v[144:145], s[4:5], 0, v[0:1]
	v_readlane_b32 s1, v254, 33
	v_sub_u32_e32 v161, v135, v137
	v_sub_u32_e32 v0, v2, v0
	v_lshlrev_b32_e32 v139, 7, v135
	v_or_b32_e32 v120, 0x200000, v114
	v_add_u32_e32 v122, 0x16000, v116
	v_or_b32_e32 v124, 0x400000, v114
	v_or_b32_e32 v128, 0x600000, v114
	v_lshlrev_b32_e32 v141, 6, v135
	s_mov_b32 s50, 0
	v_cmp_eq_u32_e64 s[44:45], 3, v7
	v_mov_b32_e32 v117, v1
	v_mov_b32_e32 v119, v1
	v_mov_b32_e32 v123, v1
	v_mov_b32_e32 v127, v1
	v_mov_b32_e32 v115, v1
	v_mov_b32_e32 v121, v1
	v_mov_b32_e32 v125, v1
	v_mov_b32_e32 v129, v1
	v_lshl_add_u32 v154, v6, 4, s49
	v_lshl_add_u32 v155, v8, 4, s49
	v_lshl_add_u32 v156, v9, 4, s49
	v_lshl_add_u32 v158, v4, 4, s49
	v_lshl_add_u32 v159, v5, 4, s49
	s_add_i32 s51, s1, s0
	v_add_u32_e32 v162, 0xffffff68, v161
	v_sub_u32_e32 v163, 0, v7
	s_add_i32 s52, s49, 0x1fb0
	v_add_u32_e32 v165, s1, v0
	s_add_i32 s53, s49, 0xc00
	s_add_i32 s54, s49, 0x1400
	s_add_i32 s55, s49, 0x1c00
	v_add_u32_e32 v214, v154, v139
	v_add_u32_e32 v215, v155, v139
	v_add_u32_e32 v216, v156, v139
	v_add_u32_e32 v217, v157, v139
	v_add_u32_e32 v218, v158, v141
	v_add_u32_e32 v219, v159, v141
	s_branch .LBB0_271

; #define LAS __attribute__((address_space(3)))
; DI void attn_dma(const AttnCtx& c, int kt) {
;     const char* kb = (const char*)(c.kg + (size_t)(kt * 32 * c.krs) * RM_LD);
;     const char* vb = (const char*)(c.vg + kt * 32);
; #pragma unroll
;     for (int j = 0; j < 4; ++j) __builtin_amdgcn_global_load_lds((const unsigned*)(kb + c.koff[j]), (LAS unsigned*)(c.wl + j * 1024), 16, 0, 0);
; #pragma unroll
;     for (int j = 0; j < 4; ++j) __builtin_amdgcn_global_load_lds((const unsigned*)(vb + c.voff[j]), (LAS unsigned*)(c.wl + 4096 + j * 1024), 16, 0, 0);
; }
; template <int MODE>
; DI void attn_range(const AttnCtx& c, const bf16x8 (&qf)[4], int lo, int hi, int t0, int d00, AttnSt& st, const unsigned* maskrow, int h8, int win, int dmask, bool lane_sel) {
;     ...
;     for (int kt = lo; kt <= hi; ++kt) {
;         asm volatile("s_waitcnt vmcnt(0)" ::: "memory");
;         bf16x8 kf[4], vf[2][2];
; #pragma unroll
;         for (int ks = 0; ks < 4; ++ks) kf[ks] = *(const LAS bf16x8*)(c.wl + c.kfo[ks]);
; #pragma unroll
;         for (int mt = 0; mt < 2; ++mt)
; #pragma unroll
;             for (int s = 0; s < 2; ++s) vf[mt][s] = *(const LAS bf16x8*)(c.wl + 4096 + c.vfo[mt][s]);
;         const unsigned W = Wn >> h8;
;         const int dlo = t0 - kt * 32 - 31;
;         float ub = 0.f; bool uni = false;
;         if (dlo >= 182) { const unsigned ua = __builtin_amdgcn_readfirstlane(__float_as_uint(c.lut[dlo])), ue = __builtin_amdgcn_readfirstlane(__float_as_uint(c.lut[dlo + 62])); uni = (ua == ue); ub = __uint_as_float(ua); }
;         asm volatile("s_waitcnt lgkmcnt(0)" ::: "memory");
;         if (kt < hi) { attn_dma(c, kt + 1); if (MODE == 0) Wn = maskrow[kt + 1]; }
.LBB0_283:
	s_waitcnt vmcnt(0)
	s_waitcnt lgkmcnt(0)
	ds_read_b128 v[106:109], v214
	ds_read_b128 v[110:113], v215
	ds_read_b128 v[102:105], v216
	ds_read_b128 v[98:101], v217
	ds_read_b128 v[94:97], v218 offset:4096
	ds_read_b128 v[86:89], v218 offset:6144
	ds_read_b128 v[90:93], v219 offset:4096
	ds_read_b128 v[82:85], v219 offset:6144
	s_waitcnt lgkmcnt(0)
	s_cmp_ge_i32 s69, s57
	s_cselect_b64 s[8:9], -1, 0
	s_and_b64 vcc, exec, s[8:9]
	s_cbranch_vccnz .LBB0_285
	s_add_i32 s7, s6, 32
	s_mul_hi_i32 s47, s7, 0x1600
	s_mulk_i32 s7, 0x1600
	s_add_u32 s46, s1, s7
	s_addc_u32 s47, s66, s47
	s_add_u32 s46, s46, s20
	s_addc_u32 s47, s47, s21
	s_mov_b32 m0, s49
	s_nop 0
	global_load_lds_dwordx4 v116, s[46:47]
	s_mov_b32 m0, s2
	s_nop 0
	global_load_lds_dwordx4 v118, s[46:47]
	s_mov_b32 m0, s70
	s_nop 0
	global_load_lds_dwordx4 v122, s[46:47]
	s_mov_b32 m0, s53
	s_nop 0
	global_load_lds_dwordx4 v126, s[46:47]
	s_ashr_i32 s7, s6, 31
	s_lshl_b64 s[46:47], s[6:7], 1
	s_add_u32 s46, s67, s46
	s_addc_u32 s47, s68, s47
	s_add_u32 s74, s46, 64
	s_addc_u32 s75, s47, 0
	s_mov_b32 m0, s71
	s_nop 0
	global_load_lds_dwordx4 v114, s[74:75]
	s_mov_b32 m0, s54
	s_nop 0
	global_load_lds_dwordx4 v120, s[74:75]
	s_mov_b32 m0, s72
	s_nop 0
	global_load_lds_dwordx4 v124, s[74:75]
	s_mov_b32 m0, s55
	s_nop 0
	global_load_lds_dwordx4 v128, s[74:75]

; #define LAS __attribute__((address_space(3)))
; DI void attn_dma(const AttnCtx& c, int kt) {
;     const char* kb = (const char*)(c.kg + (size_t)(kt * 32 * c.krs) * RM_LD);
;     const char* vb = (const char*)(c.vg + kt * 32);
; #pragma unroll
;     for (int j = 0; j < 4; ++j) __builtin_amdgcn_global_load_lds((const unsigned*)(kb + c.koff[j]), (LAS unsigned*)(c.wl + j * 1024), 16, 0, 0);
; #pragma unroll
;     for (int j = 0; j < 4; ++j) __builtin_amdgcn_global_load_lds((const unsigned*)(vb + c.voff[j]), (LAS unsigned*)(c.wl + 4096 + j * 1024), 16, 0, 0);
; }
; template <int MODE>
; DI void attn_range(const AttnCtx& c, const bf16x8 (&qf)[4], int lo, int hi, int t0, int d00, AttnSt& st, const unsigned* maskrow, int h8, int win, int dmask, bool lane_sel) {
;     ...
;     for (int kt = lo; kt <= hi; ++kt) {
;         asm volatile("s_waitcnt vmcnt(0)" ::: "memory");
;         bf16x8 kf[4], vf[2][2];
; #pragma unroll
;         for (int ks = 0; ks < 4; ++ks) kf[ks] = *(const LAS bf16x8*)(c.wl + c.kfo[ks]);
; #pragma unroll
;         for (int mt = 0; mt < 2; ++mt)
; #pragma unroll
;             for (int s = 0; s < 2; ++s) vf[mt][s] = *(const LAS bf16x8*)(c.wl + 4096 + c.vfo[mt][s]);
;         const unsigned W = Wn >> h8;
;         const int dlo = t0 - kt * 32 - 31;
;         float ub = 0.f; bool uni = false;
;         if (dlo >= 182) { const unsigned ua = __builtin_amdgcn_readfirstlane(__float_as_uint(c.lut[dlo])), ue = __builtin_amdgcn_readfirstlane(__float_as_uint(c.lut[dlo + 62])); uni = (ua == ue); ub = __uint_as_float(ua); }
;         asm volatile("s_waitcnt lgkmcnt(0)" ::: "memory");
;         if (kt < hi) { attn_dma(c, kt + 1); if (MODE == 0) Wn = maskrow[kt + 1]; }
.LBB0_302:
	s_waitcnt vmcnt(0)
	s_waitcnt lgkmcnt(0)
	ds_read_b128 v[106:109], v214
	ds_read_b128 v[110:113], v215
	ds_read_b128 v[102:105], v216
	ds_read_b128 v[98:101], v217
	ds_read_b128 v[94:97], v218 offset:4096
	ds_read_b128 v[86:89], v218 offset:6144
	ds_read_b128 v[90:93], v219 offset:4096
	ds_read_b128 v[82:85], v219 offset:6144
	s_waitcnt lgkmcnt(0)
	s_cmp_ge_i32 s66, s57
	s_cselect_b64 s[8:9], -1, 0
	s_and_b64 vcc, exec, s[8:9]
	s_cbranch_vccnz .LBB0_304
	s_add_i32 s7, s6, 32
	s_mul_hi_i32 s47, s7, 0x1600
	s_mulk_i32 s7, 0x1600
	s_add_u32 s46, s63, s7
	s_addc_u32 s47, s64, s47
	s_add_u32 s46, s46, s20
	s_addc_u32 s47, s47, s21
	s_mov_b32 m0, s49
	s_nop 0
	global_load_lds_dwordx4 v116, s[46:47]
	s_mov_b32 m0, s2
	s_nop 0
	global_load_lds_dwordx4 v118, s[46:47]
	s_mov_b32 m0, s67
	s_nop 0
	global_load_lds_dwordx4 v122, s[46:47]
	s_mov_b32 m0, s53
	s_nop 0
	global_load_lds_dwordx4 v126, s[46:47]
	s_ashr_i32 s7, s6, 31
	s_lshl_b64 s[46:47], s[6:7], 1
	s_add_u32 s46, s61, s46
	s_addc_u32 s47, s62, s47
	s_add_u32 s70, s46, 64
	s_addc_u32 s71, s47, 0
	s_mov_b32 m0, s68
	s_nop 0
	global_load_lds_dwordx4 v114, s[70:71]
	s_mov_b32 m0, s54
	s_nop 0
	global_load_lds_dwordx4 v120, s[70:71]
	s_mov_b32 m0, s69
	s_nop 0
	global_load_lds_dwordx4 v124, s[70:71]
	s_mov_b32 m0, s55
	s_nop 0
	global_load_lds_dwordx4 v128, s[70:71]

; #define LAS __attribute__((address_space(3)))
; DI void attn_dma(const AttnCtx& c, int kt) {
;     const char* kb = (const char*)(c.kg + (size_t)(kt * 32 * c.krs) * RM_LD);
;     const char* vb = (const char*)(c.vg + kt * 32);
; #pragma unroll
;     for (int j = 0; j < 4; ++j) __builtin_amdgcn_global_load_lds((const unsigned*)(kb + c.koff[j]), (LAS unsigned*)(c.wl + j * 1024), 16, 0, 0);
; #pragma unroll
;     for (int j = 0; j < 4; ++j) __builtin_amdgcn_global_load_lds((const unsigned*)(vb + c.voff[j]), (LAS unsigned*)(c.wl + 4096 + j * 1024), 16, 0, 0);
; }
; template <int MODE>
; DI void attn_range(const AttnCtx& c, const bf16x8 (&qf)[4], int lo, int hi, int t0, int d00, AttnSt& st, const unsigned* maskrow, int h8, int win, int dmask, bool lane_sel) {
;     ...
;     for (int kt = lo; kt <= hi; ++kt) {
;         asm volatile("s_waitcnt vmcnt(0)" ::: "memory");
;         bf16x8 kf[4], vf[2][2];
; #pragma unroll
;         for (int ks = 0; ks < 4; ++ks) kf[ks] = *(const LAS bf16x8*)(c.wl + c.kfo[ks]);
; #pragma unroll
;         for (int mt = 0; mt < 2; ++mt)
; #pragma unroll
;             for (int s = 0; s < 2; ++s) vf[mt][s] = *(const LAS bf16x8*)(c.wl + 4096 + c.vfo[mt][s]);
;         const unsigned W = Wn >> h8;
;         const int dlo = t0 - kt * 32 - 31;
;         float ub = 0.f; bool uni = false;
;         if (dlo >= 182) { const unsigned ua = __builtin_amdgcn_readfirstlane(__float_as_uint(c.lut[dlo])), ue = __builtin_amdgcn_readfirstlane(__float_as_uint(c.lut[dlo + 62])); uni = (ua == ue); ub = __uint_as_float(ua); }
;         asm volatile("s_waitcnt lgkmcnt(0)" ::: "memory");
;         if (kt < hi) { attn_dma(c, kt + 1); if (MODE == 0) Wn = maskrow[kt + 1]; }
.LBB0_322:
	s_waitcnt vmcnt(0)
	ds_read_b128 v[34:37], v214
	ds_read_b128 v[90:93], v215
	ds_read_b128 v[86:89], v216
	ds_read_b128 v[82:85], v217
	ds_read_b128 v[78:81], v218 offset:4096
	ds_read_b128 v[70:73], v218 offset:6144
	ds_read_b128 v[74:77], v219 offset:4096
	ds_read_b128 v[66:69], v219 offset:6144
	s_waitcnt lgkmcnt(0)
	s_cmp_ge_i32 s60, s57
	s_cbranch_scc1 .LBB0_324
	s_mul_i32 s62, s2, 0x1600
	s_mul_hi_i32 s61, s2, 0x1600
	s_add_u32 s62, s0, s62
	s_addc_u32 s63, s1, s61
	s_add_u32 s62, s62, s64
	s_addc_u32 s63, s63, s65
	s_mov_b32 m0, s49
	global_load_dword v0, v[100:101], off
	global_load_lds_dwordx4 v116, s[62:63]
	s_mov_b32 m0, s7
	s_nop 0
	global_load_lds_dwordx4 v118, s[62:63]
	s_mov_b32 m0, s9
	s_nop 0
	global_load_lds_dwordx4 v122, s[62:63]
	s_mov_b32 m0, s53
	s_nop 0
	global_load_lds_dwordx4 v126, s[62:63]
	s_lshl_b64 s[62:63], s[2:3], 1
	s_add_u32 s62, s4, s62
	s_addc_u32 s63, s5, s63
	s_mov_b32 m0, s46
	s_nop 0
	global_load_lds_dwordx4 v114, s[62:63]
	s_mov_b32 m0, s54
	s_nop 0
	global_load_lds_dwordx4 v120, s[62:63]
	s_mov_b32 m0, s47
	s_nop 0
	global_load_lds_dwordx4 v124, s[62:63]
	s_mov_b32 m0, s55
	s_nop 0
	global_load_lds_dwordx4 v128, s[62:63]

; #define LAS __attribute__((address_space(3)))
; DI void attn_dma(const AttnCtx& c, int kt) {
;     const char* kb = (const char*)(c.kg + (size_t)(kt * 32 * c.krs) * RM_LD);
;     const char* vb = (const char*)(c.vg + kt * 32);
; #pragma unroll
;     for (int j = 0; j < 4; ++j) __builtin_amdgcn_global_load_lds((const unsigned*)(kb + c.koff[j]), (LAS unsigned*)(c.wl + j * 1024), 16, 0, 0);
; #pragma unroll
;     for (int j = 0; j < 4; ++j) __builtin_amdgcn_global_load_lds((const unsigned*)(vb + c.voff[j]), (LAS unsigned*)(c.wl + 4096 + j * 1024), 16, 0, 0);
; }
; template <int MODE>
; DI void attn_range(const AttnCtx& c, const bf16x8 (&qf)[4], int lo, int hi, int t0, int d00, AttnSt& st, const unsigned* maskrow, int h8, int win, int dmask, bool lane_sel) {
;     ...
;     for (int kt = lo; kt <= hi; ++kt) {
;         asm volatile("s_waitcnt vmcnt(0)" ::: "memory");
;         bf16x8 kf[4], vf[2][2];
; #pragma unroll
;         for (int ks = 0; ks < 4; ++ks) kf[ks] = *(const LAS bf16x8*)(c.wl + c.kfo[ks]);
; #pragma unroll
;         for (int mt = 0; mt < 2; ++mt)
; #pragma unroll
;             for (int s = 0; s < 2; ++s) vf[mt][s] = *(const LAS bf16x8*)(c.wl + 4096 + c.vfo[mt][s]);
;         const unsigned W = Wn >> h8;
;         const int dlo = t0 - kt * 32 - 31;
;         float ub = 0.f; bool uni = false;
;         if (dlo >= 182) { const unsigned ua = __builtin_amdgcn_readfirstlane(__float_as_uint(c.lut[dlo])), ue = __builtin_amdgcn_readfirstlane(__float_as_uint(c.lut[dlo + 62])); uni = (ua == ue); ub = __uint_as_float(ua); }
;         asm volatile("s_waitcnt lgkmcnt(0)" ::: "memory");
;         if (kt < hi) { attn_dma(c, kt + 1); if (MODE == 0) Wn = maskrow[kt + 1]; }
.LBB0_347:
	s_waitcnt vmcnt(0)
	ds_read_b128 v[50:53], v214
	ds_read_b128 v[90:93], v215
	ds_read_b128 v[94:97], v216
	ds_read_b128 v[86:89], v217
	ds_read_b128 v[82:85], v218 offset:4096
	ds_read_b128 v[6:9], v218 offset:6144
	ds_read_b128 v[10:13], v219 offset:4096
	ds_read_b128 v[2:5], v219 offset:6144
	s_waitcnt lgkmcnt(0)
	s_cmp_ge_u32 s60, s61
	s_cbranch_scc1 .LBB0_349
	s_ashr_i32 s7, s6, 31
	s_mul_i32 s66, s6, 0x1600
	s_mul_hi_i32 s67, s6, 0x1600
	s_add_u32 s66, s46, s66
	s_addc_u32 s67, s47, s67
	s_mov_b32 m0, s49
	s_nop 0
	global_load_lds_dwordx4 v116, s[66:67]
	s_mov_b32 m0, s62
	s_nop 0
	global_load_lds_dwordx4 v118, s[66:67]
	s_mov_b32 m0, s63
	s_nop 0
	global_load_lds_dwordx4 v122, s[66:67]
	s_mov_b32 m0, s53
	s_nop 0
	global_load_lds_dwordx4 v126, s[66:67]
	s_lshl_b64 s[66:67], s[6:7], 1
	s_add_u32 s68, s4, s66
	s_addc_u32 s69, s5, s67
	s_mov_b32 m0, s2
	s_nop 0
	global_load_lds_dwordx4 v114, s[68:69]
	s_mov_b32 m0, s54
	s_nop 0
	global_load_lds_dwordx4 v120, s[68:69]
	s_mov_b32 m0, s64
	s_nop 0
	global_load_lds_dwordx4 v124, s[68:69]
	s_mov_b32 m0, s55
	s_nop 0
	global_load_lds_dwordx4 v128, s[68:69]

; #define LAS __attribute__((address_space(3)))
; DI void attn_dma(const AttnCtx& c, int kt) {
;     const char* kb = (const char*)(c.kg + (size_t)(kt * 32 * c.krs) * RM_LD);
;     const char* vb = (const char*)(c.vg + kt * 32);
; #pragma unroll
;     for (int j = 0; j < 4; ++j) __builtin_amdgcn_global_load_lds((const unsigned*)(kb + c.koff[j]), (LAS unsigned*)(c.wl + j * 1024), 16, 0, 0);
; #pragma unroll
;     for (int j = 0; j < 4; ++j) __builtin_amdgcn_global_load_lds((const unsigned*)(vb + c.voff[j]), (LAS unsigned*)(c.wl + 4096 + j * 1024), 16, 0, 0);
; }
; template <int MODE>
; DI void attn_range(const AttnCtx& c, const bf16x8 (&qf)[4], int lo, int hi, int t0, int d00, AttnSt& st, const unsigned* maskrow, int h8, int win, int dmask, bool lane_sel) {
;     ...
;     for (int kt = lo; kt <= hi; ++kt) {
;         asm volatile("s_waitcnt vmcnt(0)" ::: "memory");
;         bf16x8 kf[4], vf[2][2];
; #pragma unroll
;         for (int ks = 0; ks < 4; ++ks) kf[ks] = *(const LAS bf16x8*)(c.wl + c.kfo[ks]);
; #pragma unroll
;         for (int mt = 0; mt < 2; ++mt)
; #pragma unroll
;             for (int s = 0; s < 2; ++s) vf[mt][s] = *(const LAS bf16x8*)(c.wl + 4096 + c.vfo[mt][s]);
;         const unsigned W = Wn >> h8;
;         const int dlo = t0 - kt * 32 - 31;
;         float ub = 0.f; bool uni = false;
;         if (dlo >= 182) { const unsigned ua = __builtin_amdgcn_readfirstlane(__float_as_uint(c.lut[dlo])), ue = __builtin_amdgcn_readfirstlane(__float_as_uint(c.lut[dlo + 62])); uni = (ua == ue); ub = __uint_as_float(ua); }
;         asm volatile("s_waitcnt lgkmcnt(0)" ::: "memory");
;         if (kt < hi) { attn_dma(c, kt + 1); if (MODE == 0) Wn = maskrow[kt + 1]; }
.LBB0_359:
	s_waitcnt vmcnt(0)
	ds_read_b128 v[50:53], v214
	ds_read_b128 v[90:93], v215
	ds_read_b128 v[94:97], v216
	ds_read_b128 v[86:89], v217
	ds_read_b128 v[82:85], v218 offset:4096
	ds_read_b128 v[6:9], v218 offset:6144
	ds_read_b128 v[10:13], v219 offset:4096
	ds_read_b128 v[2:5], v219 offset:6144
	s_waitcnt lgkmcnt(0)
	s_cmp_ge_i32 s2, s57
	s_cselect_b64 s[6:7], -1, 0
	s_and_b64 vcc, exec, s[6:7]
	s_cbranch_vccnz .LBB0_361
	s_ashr_i32 s1, s0, 31
	s_mul_i32 s61, s0, 0x1600
	s_mul_hi_i32 s8, s0, 0x1600
	s_add_u32 s62, s46, s61
	s_addc_u32 s63, s47, s8
	s_mov_b32 m0, s49
	s_nop 0
	global_load_lds_dwordx4 v116, s[62:63]
	s_mov_b32 m0, s9
	s_nop 0
	global_load_lds_dwordx4 v118, s[62:63]
	s_mov_b32 m0, s58
	s_nop 0
	global_load_lds_dwordx4 v122, s[62:63]
	s_mov_b32 m0, s53
	s_nop 0
	global_load_lds_dwordx4 v126, s[62:63]
	s_lshl_b64 s[62:63], s[0:1], 1
	s_add_u32 s64, s4, s62
	s_addc_u32 s65, s5, s63
	s_mov_b32 m0, s59
	s_nop 0
	global_load_lds_dwordx4 v114, s[64:65]
	s_mov_b32 m0, s54
	s_nop 0
	global_load_lds_dwordx4 v120, s[64:65]
	s_mov_b32 m0, s60
	s_nop 0
	global_load_lds_dwordx4 v124, s[64:65]
	s_mov_b32 m0, s55
	s_nop 0
	global_load_lds_dwordx4 v128, s[64:65]
